# P8 and P6 pool-up epilogues: one-dword touch loads of the second half's sig/merged tiles issued with the first half's loads
# baseline (speedup 1.0000x reference)
.LBB0_956:
	v_lshl_or_b32 v144, s65, 8, v156
	v_lshl_add_u32 v150, s52, 8, v154
	v_ashrrev_i32_e32 v145, 31, v144
	v_lshlrev_b64 v[144:145], 1, v[144:145]
	v_ashrrev_i32_e32 v151, 31, v150
	v_lshl_add_u64 v[146:147], s[22:23], 0, v[144:145]
	v_lshlrev_b64 v[148:149], 11, v[150:151]
	v_lshl_add_u64 v[152:153], v[146:147], 0, v[148:149]
	v_add_u32_e32 v232, v144, v148
	v_add_u32_e32 v233, 0x8000, v232
	v_add_u32_e32 v234, 0x10000, v232
	v_add_u32_e32 v235, 0x18000, v232
	v_add_u32_e32 v232, 0x40000, v232
	v_add_u32_e32 v233, 0x40000, v233
	v_add_u32_e32 v234, 0x40000, v234
	v_add_u32_e32 v235, 0x40000, v235
	global_load_dword v241, v232, s[22:23]
	global_load_dword v241, v232, s[22:23] offset:256
	global_load_dword v241, v233, s[22:23]
	global_load_dword v241, v233, s[22:23] offset:256
	global_load_dword v241, v234, s[22:23]
	global_load_dword v241, v234, s[22:23] offset:256
	global_load_dword v241, v235, s[22:23]
	global_load_dword v241, v235, s[22:23] offset:256
	global_load_dwordx4 v[160:163], v[152:153], off
	global_load_dwordx4 v[164:167], v[152:153], off offset:256
	v_or_b32_e32 v152, 16, v150
	v_ashrrev_i32_e32 v153, 31, v152
	v_lshlrev_b64 v[180:181], 11, v[152:153]
	v_lshl_add_u64 v[152:153], v[146:147], 0, v[180:181]
	global_load_dwordx4 v[168:171], v[152:153], off
	global_load_dwordx4 v[172:175], v[152:153], off offset:256
	v_or_b32_e32 v152, 32, v150
	v_ashrrev_i32_e32 v153, 31, v152
	v_lshlrev_b64 v[152:153], 11, v[152:153]
	v_lshl_add_u64 v[182:183], v[146:147], 0, v[152:153]
	global_load_dwordx4 v[176:179], v[182:183], off
	v_or_b32_e32 v150, 48, v150
	v_ashrrev_i32_e32 v151, 31, v150
	v_lshlrev_b64 v[150:151], 11, v[150:151]
	v_lshl_add_u64 v[184:185], s[24:25], 0, v[148:149]
	v_lshl_add_u64 v[190:191], v[146:147], 0, v[150:151]
	v_lshl_add_u64 v[194:195], v[184:185], 0, v[144:145]
	v_lshl_add_u64 v[196:197], s[24:25], 0, v[180:181]
	global_load_dwordx4 v[180:183], v[182:183], off offset:256
	s_nop 0
	global_load_dwordx4 v[184:187], v[190:191], off
	s_nop 0
	global_load_dwordx4 v[190:193], v[190:191], off offset:256
	v_lshl_add_u64 v[196:197], v[196:197], 0, v[144:145]
	s_andn2_b64 vcc, exec, s[0:1]
	s_mov_b64 s[0:1], -1
	s_waitcnt vmcnt(0)
	v_lshlrev_b32_e32 v198, 16, v160
	v_and_b32_e32 v199, 0xffff0000, v160
	v_lshlrev_b32_e32 v160, 16, v161
	v_and_b32_e32 v161, 0xffff0000, v161
	v_lshlrev_b32_e32 v200, 16, v162
	v_and_b32_e32 v201, 0xffff0000, v162
	v_lshlrev_b32_e32 v162, 16, v163
	v_and_b32_e32 v163, 0xffff0000, v163
	v_lshlrev_b32_e32 v204, 16, v166
	v_and_b32_e32 v205, 0xffff0000, v166
	v_lshlrev_b32_e32 v202, 16, v164
	v_and_b32_e32 v203, 0xffff0000, v164
	v_lshlrev_b32_e32 v164, 16, v165
	v_and_b32_e32 v165, 0xffff0000, v165
	v_lshlrev_b32_e32 v166, 16, v167
	v_and_b32_e32 v167, 0xffff0000, v167
	v_pk_mul_f32 v[126:127], v[126:127], v[160:161]
	v_pk_mul_f32 v[124:125], v[124:125], v[198:199]
	v_pk_mul_f32 v[122:123], v[122:123], v[162:163]
	v_pk_mul_f32 v[162:163], v[104:105], v[204:205]
	v_cvt_pk_bf16_f32 v104, v124, v125
	v_cvt_pk_bf16_f32 v105, v126, v127
	v_lshlrev_b32_e32 v206, 16, v168
	v_and_b32_e32 v207, 0xffff0000, v168
	v_lshlrev_b32_e32 v168, 16, v169
	v_and_b32_e32 v169, 0xffff0000, v169
	v_pk_mul_f32 v[120:121], v[120:121], v[200:201]
	v_pk_mul_f32 v[110:111], v[110:111], v[164:165]
	v_pk_mul_f32 v[108:109], v[108:109], v[202:203]
	v_pk_mul_f32 v[160:161], v[106:107], v[166:167]
	v_cvt_pk_bf16_f32 v106, v120, v121
	v_cvt_pk_bf16_f32 v107, v122, v123
	global_store_dwordx4 v[194:195], v[104:107], off
	v_lshlrev_b32_e32 v208, 16, v170
	v_and_b32_e32 v209, 0xffff0000, v170
	v_cvt_pk_bf16_f32 v104, v108, v109
	v_cvt_pk_bf16_f32 v105, v110, v111
	v_lshlrev_b32_e32 v170, 16, v171
	v_and_b32_e32 v171, 0xffff0000, v171
	v_lshlrev_b32_e32 v210, 16, v172
	v_and_b32_e32 v211, 0xffff0000, v172
	v_lshlrev_b32_e32 v172, 16, v173
	v_and_b32_e32 v173, 0xffff0000, v173
	v_lshlrev_b32_e32 v212, 16, v174
	v_and_b32_e32 v213, 0xffff0000, v174
	v_lshlrev_b32_e32 v174, 16, v175
	v_and_b32_e32 v175, 0xffff0000, v175
	v_pk_mul_f32 v[118:119], v[118:119], v[168:169]
	v_pk_mul_f32 v[116:117], v[116:117], v[206:207]
	v_cvt_pk_bf16_f32 v106, v162, v163
	v_cvt_pk_bf16_f32 v107, v160, v161
	global_store_dwordx4 v[194:195], v[104:107], off offset:256
	v_pk_mul_f32 v[114:115], v[114:115], v[170:171]
	v_pk_mul_f32 v[112:113], v[112:113], v[208:209]
	v_cvt_pk_bf16_f32 v104, v116, v117
	v_cvt_pk_bf16_f32 v105, v118, v119
	v_pk_mul_f32 v[102:103], v[102:103], v[172:173]
	v_cvt_pk_bf16_f32 v106, v112, v113
	v_cvt_pk_bf16_f32 v107, v114, v115
	global_store_dwordx4 v[196:197], v[104:107], off
	v_pk_mul_f32 v[100:101], v[100:101], v[210:211]
	s_nop 0
	v_pk_mul_f32 v[104:105], v[98:99], v[174:175]
	v_pk_mul_f32 v[98:99], v[96:97], v[212:213]
	v_cvt_pk_bf16_f32 v96, v100, v101
	v_cvt_pk_bf16_f32 v97, v102, v103
	v_lshlrev_b32_e32 v100, 16, v178
	v_cvt_pk_bf16_f32 v98, v98, v99
	v_cvt_pk_bf16_f32 v99, v104, v105
	global_store_dwordx4 v[196:197], v[96:99], off offset:256
	v_and_b32_e32 v101, 0xffff0000, v178
	v_lshlrev_b32_e32 v102, 16, v179
	v_lshlrev_b32_e32 v96, 16, v176
	v_and_b32_e32 v97, 0xffff0000, v176
	v_and_b32_e32 v103, 0xffff0000, v179
	v_pk_mul_f32 v[92:93], v[92:93], v[96:97]
	v_lshlrev_b32_e32 v98, 16, v177
	v_and_b32_e32 v99, 0xffff0000, v177
	v_pk_mul_f32 v[96:97], v[90:91], v[102:103]
	v_pk_mul_f32 v[90:91], v[88:89], v[100:101]
	v_cvt_pk_bf16_f32 v88, v92, v93
	v_lshl_add_u64 v[92:93], s[24:25], 0, v[152:153]
	v_pk_mul_f32 v[94:95], v[94:95], v[98:99]
	v_lshl_add_u64 v[92:93], v[92:93], 0, v[144:145]
	v_cvt_pk_bf16_f32 v89, v94, v95
	v_cvt_pk_bf16_f32 v90, v90, v91
	v_cvt_pk_bf16_f32 v91, v96, v97
	global_store_dwordx4 v[92:93], v[88:91], off
	v_lshlrev_b32_e32 v94, 16, v182
	v_and_b32_e32 v95, 0xffff0000, v182
	v_lshlrev_b32_e32 v88, 16, v180
	v_and_b32_e32 v89, 0xffff0000, v180
	v_lshlrev_b32_e32 v90, 16, v181
	v_and_b32_e32 v91, 0xffff0000, v181
	v_lshlrev_b32_e32 v96, 16, v183
	v_and_b32_e32 v97, 0xffff0000, v183
	v_pk_mul_f32 v[86:87], v[86:87], v[90:91]
	v_pk_mul_f32 v[84:85], v[84:85], v[88:89]
	v_pk_mul_f32 v[88:89], v[82:83], v[96:97]
	v_pk_mul_f32 v[82:83], v[80:81], v[94:95]
	v_cvt_pk_bf16_f32 v80, v84, v85
	v_cvt_pk_bf16_f32 v81, v86, v87
	v_lshlrev_b32_e32 v84, 16, v186
	v_cvt_pk_bf16_f32 v82, v82, v83
	v_cvt_pk_bf16_f32 v83, v88, v89
	global_store_dwordx4 v[92:93], v[80:83], off offset:256
	v_and_b32_e32 v85, 0xffff0000, v186
	v_lshlrev_b32_e32 v86, 16, v187
	v_lshlrev_b32_e32 v80, 16, v184
	v_and_b32_e32 v81, 0xffff0000, v184
	v_and_b32_e32 v87, 0xffff0000, v187
	v_pk_mul_f32 v[76:77], v[76:77], v[80:81]
	v_lshlrev_b32_e32 v82, 16, v185
	v_and_b32_e32 v83, 0xffff0000, v185
	v_pk_mul_f32 v[80:81], v[74:75], v[86:87]
	v_pk_mul_f32 v[74:75], v[72:73], v[84:85]
	v_cvt_pk_bf16_f32 v72, v76, v77
	v_lshl_add_u64 v[76:77], s[24:25], 0, v[150:151]
	v_pk_mul_f32 v[78:79], v[78:79], v[82:83]
	v_lshl_add_u64 v[94:95], v[76:77], 0, v[144:145]
	v_cvt_pk_bf16_f32 v73, v78, v79
	v_cvt_pk_bf16_f32 v74, v74, v75
	v_cvt_pk_bf16_f32 v75, v80, v81
	global_store_dwordx4 v[94:95], v[72:75], off
	v_lshlrev_b32_e32 v76, 16, v192
	v_and_b32_e32 v77, 0xffff0000, v192
	v_lshlrev_b32_e32 v72, 16, v190
	v_and_b32_e32 v73, 0xffff0000, v190
	v_lshlrev_b32_e32 v78, 16, v193
	v_and_b32_e32 v79, 0xffff0000, v193
	v_pk_mul_f32 v[68:69], v[68:69], v[72:73]
	v_lshl_add_u64 v[98:99], v[148:149], 0, s[18:19]
	v_lshlrev_b32_e32 v74, 16, v191
	v_and_b32_e32 v75, 0xffff0000, v191
	v_pk_mul_f32 v[72:73], v[66:67], v[78:79]
	v_pk_mul_f32 v[66:67], v[64:65], v[76:77]
	v_cvt_pk_bf16_f32 v64, v68, v69
	v_lshl_add_u64 v[68:69], v[146:147], 0, v[98:99]
	v_pk_mul_f32 v[70:71], v[70:71], v[74:75]
	v_lshl_add_u64 v[100:101], v[148:149], 0, s[36:37]
	v_cvt_pk_bf16_f32 v65, v70, v71
	v_cvt_pk_bf16_f32 v66, v66, v67
	v_cvt_pk_bf16_f32 v67, v72, v73
	global_load_dwordx4 v[74:77], v[68:69], off
	global_load_dwordx4 v[78:81], v[68:69], off offset:256
	v_lshl_add_u64 v[68:69], v[146:147], 0, v[100:101]
	global_load_dwordx4 v[82:85], v[68:69], off
	global_load_dwordx4 v[86:89], v[68:69], off offset:256
	v_lshl_add_u64 v[102:103], v[148:149], 0, s[38:39]
	v_lshl_add_u64 v[68:69], v[146:147], 0, v[102:103]
	global_load_dwordx4 v[90:93], v[68:69], off
	v_lshl_add_u64 v[72:73], v[148:149], 0, s[40:41]
	global_store_dwordx4 v[94:95], v[64:67], off offset:256
	global_load_dwordx4 v[94:97], v[68:69], off offset:256
	s_waitcnt vmcnt(6)
	v_lshlrev_b32_e32 v104, 16, v74
	v_lshl_add_u64 v[64:65], v[146:147], 0, v[72:73]
	global_load_dwordx4 v[68:71], v[64:65], off
	s_nop 0
	global_load_dwordx4 v[64:67], v[64:65], off offset:256
	v_and_b32_e32 v105, 0xffff0000, v74
	v_lshlrev_b32_e32 v74, 16, v75
	v_and_b32_e32 v75, 0xffff0000, v75
	v_lshlrev_b32_e32 v106, 16, v76
	v_and_b32_e32 v107, 0xffff0000, v76
	v_lshlrev_b32_e32 v76, 16, v77
	v_and_b32_e32 v77, 0xffff0000, v77
	v_pk_mul_f32 v[60:61], v[60:61], v[104:105]
	v_pk_mul_f32 v[62:63], v[62:63], v[74:75]
	v_pk_mul_f32 v[74:75], v[58:59], v[76:77]
	v_pk_mul_f32 v[58:59], v[56:57], v[106:107]
	v_cvt_pk_bf16_f32 v56, v60, v61
	v_lshl_add_u64 v[60:61], s[24:25], 0, v[98:99]
	v_cvt_pk_bf16_f32 v57, v62, v63
	v_cvt_pk_bf16_f32 v58, v58, v59
	v_cvt_pk_bf16_f32 v59, v74, v75
	v_lshl_add_u64 v[60:61], v[60:61], 0, v[144:145]
	global_store_dwordx4 v[60:61], v[56:59], off
	s_waitcnt vmcnt(8)
	v_lshlrev_b32_e32 v62, 16, v80
	v_and_b32_e32 v63, 0xffff0000, v80
	v_lshlrev_b32_e32 v56, 16, v78
	v_and_b32_e32 v57, 0xffff0000, v78
	v_lshlrev_b32_e32 v58, 16, v79
	v_and_b32_e32 v59, 0xffff0000, v79
	v_lshlrev_b32_e32 v74, 16, v81
	v_and_b32_e32 v75, 0xffff0000, v81
	v_pk_mul_f32 v[54:55], v[54:55], v[58:59]
	v_pk_mul_f32 v[52:53], v[52:53], v[56:57]
	v_pk_mul_f32 v[56:57], v[50:51], v[74:75]
	v_pk_mul_f32 v[50:51], v[48:49], v[62:63]
	v_cvt_pk_bf16_f32 v48, v52, v53
	v_cvt_pk_bf16_f32 v49, v54, v55
	s_waitcnt vmcnt(7)
	v_lshlrev_b32_e32 v52, 16, v84
	v_cvt_pk_bf16_f32 v50, v50, v51
	v_cvt_pk_bf16_f32 v51, v56, v57
	global_store_dwordx4 v[60:61], v[48:51], off offset:256
	v_and_b32_e32 v53, 0xffff0000, v84
	v_lshlrev_b32_e32 v54, 16, v85
	v_lshlrev_b32_e32 v48, 16, v82
	v_and_b32_e32 v49, 0xffff0000, v82
	v_and_b32_e32 v55, 0xffff0000, v85
	v_pk_mul_f32 v[44:45], v[44:45], v[48:49]
	v_lshlrev_b32_e32 v50, 16, v83
	v_and_b32_e32 v51, 0xffff0000, v83
	v_pk_mul_f32 v[48:49], v[42:43], v[54:55]
	v_pk_mul_f32 v[42:43], v[40:41], v[52:53]
	v_cvt_pk_bf16_f32 v40, v44, v45
	v_lshl_add_u64 v[44:45], s[24:25], 0, v[100:101]
	v_pk_mul_f32 v[46:47], v[46:47], v[50:51]
	v_lshl_add_u64 v[44:45], v[44:45], 0, v[144:145]
	v_cvt_pk_bf16_f32 v41, v46, v47
	v_cvt_pk_bf16_f32 v42, v42, v43
	v_cvt_pk_bf16_f32 v43, v48, v49
	global_store_dwordx4 v[44:45], v[40:43], off
	s_waitcnt vmcnt(8)
	v_lshlrev_b32_e32 v46, 16, v88
	v_and_b32_e32 v47, 0xffff0000, v88
	v_lshlrev_b32_e32 v40, 16, v86
	v_and_b32_e32 v41, 0xffff0000, v86
	v_lshlrev_b32_e32 v42, 16, v87
	v_and_b32_e32 v43, 0xffff0000, v87
	v_lshlrev_b32_e32 v48, 16, v89
	v_and_b32_e32 v49, 0xffff0000, v89
	v_pk_mul_f32 v[38:39], v[38:39], v[42:43]
	v_pk_mul_f32 v[36:37], v[36:37], v[40:41]
	v_pk_mul_f32 v[40:41], v[34:35], v[48:49]
	v_pk_mul_f32 v[34:35], v[32:33], v[46:47]
	v_cvt_pk_bf16_f32 v32, v36, v37
	v_cvt_pk_bf16_f32 v33, v38, v39
	s_waitcnt vmcnt(7)
	v_lshlrev_b32_e32 v36, 16, v92
	v_cvt_pk_bf16_f32 v34, v34, v35
	v_cvt_pk_bf16_f32 v35, v40, v41
	global_store_dwordx4 v[44:45], v[32:35], off offset:256
	v_and_b32_e32 v37, 0xffff0000, v92
	v_lshlrev_b32_e32 v38, 16, v93
	v_lshlrev_b32_e32 v32, 16, v90
	v_and_b32_e32 v33, 0xffff0000, v90
	v_and_b32_e32 v39, 0xffff0000, v93
	v_pk_mul_f32 v[28:29], v[28:29], v[32:33]
	v_lshlrev_b32_e32 v34, 16, v91
	v_and_b32_e32 v35, 0xffff0000, v91
	v_pk_mul_f32 v[32:33], v[26:27], v[38:39]
	v_pk_mul_f32 v[26:27], v[24:25], v[36:37]
	v_cvt_pk_bf16_f32 v24, v28, v29
	v_lshl_add_u64 v[28:29], s[24:25], 0, v[102:103]
	v_pk_mul_f32 v[30:31], v[30:31], v[34:35]
	v_lshl_add_u64 v[28:29], v[28:29], 0, v[144:145]
	v_cvt_pk_bf16_f32 v25, v30, v31
	v_cvt_pk_bf16_f32 v26, v26, v27
	v_cvt_pk_bf16_f32 v27, v32, v33
	global_store_dwordx4 v[28:29], v[24:27], off
	s_waitcnt vmcnt(7)
	v_lshlrev_b32_e32 v30, 16, v96
	v_and_b32_e32 v31, 0xffff0000, v96
	v_lshlrev_b32_e32 v24, 16, v94
	v_and_b32_e32 v25, 0xffff0000, v94
	v_lshlrev_b32_e32 v26, 16, v95
	v_and_b32_e32 v27, 0xffff0000, v95
	v_lshlrev_b32_e32 v32, 16, v97
	v_and_b32_e32 v33, 0xffff0000, v97
	v_pk_mul_f32 v[22:23], v[22:23], v[26:27]
	v_pk_mul_f32 v[20:21], v[20:21], v[24:25]
	v_pk_mul_f32 v[24:25], v[18:19], v[32:33]
	v_pk_mul_f32 v[18:19], v[16:17], v[30:31]
	v_cvt_pk_bf16_f32 v16, v20, v21
	v_cvt_pk_bf16_f32 v17, v22, v23
	s_waitcnt vmcnt(6)
	v_lshlrev_b32_e32 v20, 16, v70
	v_cvt_pk_bf16_f32 v18, v18, v19
	v_cvt_pk_bf16_f32 v19, v24, v25
	global_store_dwordx4 v[28:29], v[16:19], off offset:256
	v_and_b32_e32 v21, 0xffff0000, v70
	v_lshlrev_b32_e32 v22, 16, v71
	v_lshlrev_b32_e32 v16, 16, v68
	v_and_b32_e32 v17, 0xffff0000, v68
	v_and_b32_e32 v23, 0xffff0000, v71
	v_pk_mul_f32 v[12:13], v[12:13], v[16:17]
	v_lshlrev_b32_e32 v18, 16, v69
	v_and_b32_e32 v19, 0xffff0000, v69
	v_pk_mul_f32 v[16:17], v[10:11], v[22:23]
	v_pk_mul_f32 v[10:11], v[8:9], v[20:21]
	v_cvt_pk_bf16_f32 v8, v12, v13
	v_lshl_add_u64 v[12:13], s[24:25], 0, v[72:73]
	v_pk_mul_f32 v[14:15], v[14:15], v[18:19]
	v_lshl_add_u64 v[12:13], v[12:13], 0, v[144:145]
	v_cvt_pk_bf16_f32 v9, v14, v15
	v_cvt_pk_bf16_f32 v10, v10, v11
	v_cvt_pk_bf16_f32 v11, v16, v17
	global_store_dwordx4 v[12:13], v[8:11], off
	s_waitcnt vmcnt(7)
	v_lshlrev_b32_e32 v14, 16, v66
	v_and_b32_e32 v15, 0xffff0000, v66
	v_lshlrev_b32_e32 v8, 16, v64
	v_and_b32_e32 v9, 0xffff0000, v64
	v_lshlrev_b32_e32 v16, 16, v67
	v_and_b32_e32 v17, 0xffff0000, v67
	v_lshlrev_b32_e32 v10, 16, v65
	v_and_b32_e32 v11, 0xffff0000, v65
	v_pk_mul_f32 v[4:5], v[4:5], v[8:9]
	v_pk_mul_f32 v[8:9], v[2:3], v[16:17]
	v_pk_mul_f32 v[2:3], v[0:1], v[14:15]
	v_pk_mul_f32 v[6:7], v[6:7], v[10:11]
	v_cvt_pk_bf16_f32 v0, v4, v5
	s_nop 0
	v_cvt_pk_bf16_f32 v1, v6, v7
	v_cvt_pk_bf16_f32 v2, v2, v3
	v_cvt_pk_bf16_f32 v3, v8, v9
	global_store_dwordx4 v[12:13], v[0:3], off offset:256
	s_cbranch_vccnz .LBB0_945
	s_andn2_b64 vcc, exec, s[10:11]
	s_cbranch_vccnz .LBB0_944
	s_barrier
	s_branch .LBB0_944

.LBB0_1029:
	ds_read_b128 v[128:131], v169
	ds_read_b128 v[132:135], v169 offset:1024
	ds_read_b128 v[136:139], v169 offset:2048
	ds_read_b128 v[140:143], v169 offset:3072
	ds_read_b128 v[160:163], v170
	ds_read_b128 v[172:175], v170 offset:1024
	ds_read_b128 v[176:179], v170 offset:2048
	ds_read_b128 v[180:183], v170 offset:3072
	s_add_u32 s28, s44, 0xfffe0080
	s_addc_u32 s29, s45, -1
	s_cmp_eq_u32 s64, 4
	s_cselect_b32 s51, s37, s29
	s_cselect_b32 s50, s60, s28
	s_cselect_b32 s47, s19, s63
	s_cselect_b32 s46, s61, s62
	v_lshl_add_u64 v[164:165], s[44:45], 0, v[152:153]
	s_add_i32 m0, s17, 0xc000
	ds_read_b128 v[184:187], v171
	ds_read_b128 v[190:193], v171 offset:1024
	ds_read_b128 v[194:197], v171 offset:2048
	ds_read_b128 v[198:201], v171 offset:3072
	ds_read_b128 v[202:205], v171 offset:4096
	ds_read_b128 v[206:209], v171 offset:5120
	ds_read_b128 v[210:213], v171 offset:6144
	ds_read_b128 v[214:217], v171 offset:7168
	global_load_lds_dwordx4 v[164:165], off
	v_lshl_add_u64 v[164:165], s[44:45], 0, v[154:155]
	s_add_i32 m0, s17, 0xe000
	s_nop 0
	global_load_lds_dwordx4 v[164:165], off
	s_waitcnt vmcnt(8)
	s_waitcnt lgkmcnt(0)
	s_nop 0
	s_barrier
	s_waitcnt lgkmcnt(0)
	v_mfma_f32_16x16x32_bf16 v[124:127], v[128:131], v[184:187], v[124:127]
	v_mfma_f32_16x16x32_bf16 v[120:123], v[136:139], v[184:187], v[120:123]
	v_mfma_f32_16x16x32_bf16 v[116:119], v[128:131], v[194:197], v[116:119]
	v_mfma_f32_16x16x32_bf16 v[112:115], v[136:139], v[194:197], v[112:115]
	v_mfma_f32_16x16x32_bf16 v[92:95], v[128:131], v[202:205], v[92:95]
	v_mfma_f32_16x16x32_bf16 v[84:87], v[136:139], v[202:205], v[84:87]
	v_mfma_f32_16x16x32_bf16 v[76:79], v[128:131], v[210:213], v[76:79]
	v_mfma_f32_16x16x32_bf16 v[68:71], v[136:139], v[210:213], v[68:71]
	v_mfma_f32_16x16x32_bf16 v[124:127], v[132:135], v[190:193], v[124:127]
	v_mfma_f32_16x16x32_bf16 v[120:123], v[140:143], v[190:193], v[120:123]
	v_mfma_f32_16x16x32_bf16 v[116:119], v[132:135], v[198:201], v[116:119]
	v_mfma_f32_16x16x32_bf16 v[112:115], v[140:143], v[198:201], v[112:115]
	v_mfma_f32_16x16x32_bf16 v[92:95], v[132:135], v[206:209], v[92:95]
	v_mfma_f32_16x16x32_bf16 v[84:87], v[140:143], v[206:209], v[84:87]
	v_mfma_f32_16x16x32_bf16 v[76:79], v[132:135], v[214:217], v[76:79]
	v_mfma_f32_16x16x32_bf16 v[68:71], v[140:143], v[214:217], v[68:71]
	v_mfma_f32_16x16x32_bf16 v[108:111], v[160:163], v[184:187], v[108:111]
	v_mfma_f32_16x16x32_bf16 v[104:107], v[176:179], v[184:187], v[104:107]
	v_mfma_f32_16x16x32_bf16 v[100:103], v[160:163], v[194:197], v[100:103]
	v_mfma_f32_16x16x32_bf16 v[96:99], v[176:179], v[194:197], v[96:99]
	v_mfma_f32_16x16x32_bf16 v[88:91], v[160:163], v[202:205], v[88:91]
	v_mfma_f32_16x16x32_bf16 v[80:83], v[176:179], v[202:205], v[80:83]
	v_mfma_f32_16x16x32_bf16 v[72:75], v[160:163], v[210:213], v[72:75]
	v_mfma_f32_16x16x32_bf16 v[64:67], v[176:179], v[210:213], v[64:67]
	v_mfma_f32_16x16x32_bf16 v[108:111], v[172:175], v[190:193], v[108:111]
	v_mfma_f32_16x16x32_bf16 v[104:107], v[180:183], v[190:193], v[104:107]
	v_mfma_f32_16x16x32_bf16 v[100:103], v[172:175], v[198:201], v[100:103]
	v_mfma_f32_16x16x32_bf16 v[96:99], v[180:183], v[198:201], v[96:99]
	v_mfma_f32_16x16x32_bf16 v[88:91], v[172:175], v[206:209], v[88:91]
	v_mfma_f32_16x16x32_bf16 v[80:83], v[180:183], v[206:209], v[80:83]
	v_mfma_f32_16x16x32_bf16 v[72:75], v[172:175], v[214:217], v[72:75]
	v_mfma_f32_16x16x32_bf16 v[64:67], v[180:183], v[214:217], v[64:67]
	s_barrier
	s_add_i32 s28, s54, s13
	v_lshl_add_u64 v[164:165], s[46:47], 0, v[146:147]
	s_mov_b32 m0, s28
	ds_read_b128 v[184:187], v171 offset:16384
	ds_read_b128 v[190:193], v171 offset:17408
	ds_read_b128 v[194:197], v171 offset:18432
	ds_read_b128 v[198:201], v171 offset:19456
	ds_read_b128 v[202:205], v171 offset:20480
	ds_read_b128 v[206:209], v171 offset:21504
	ds_read_b128 v[210:213], v171 offset:22528
	ds_read_b128 v[214:217], v171 offset:23552
	global_load_lds_dwordx4 v[164:165], off
	s_add_i32 m0, s28, 0x2000
	s_add_u32 s28, s46, 0x20000
	v_lshl_add_u64 v[218:219], s[46:47], 0, v[150:151]
	s_addc_u32 s29, s47, 0
	s_add_i32 s33, s55, s13
	global_load_lds_dwordx4 v[218:219], off
	v_lshl_add_u64 v[220:221], s[28:29], 0, v[146:147]
	s_mov_b32 m0, s33
	v_lshl_add_u64 v[222:223], s[50:51], 0, v[148:149]
	global_load_lds_dwordx4 v[220:221], off
	v_lshl_add_u64 v[220:221], s[28:29], 0, v[150:151]
	s_add_i32 m0, s33, 0x2000
	s_nop 0
	global_load_lds_dwordx4 v[220:221], off
	v_lshl_add_u64 v[220:221], s[50:51], 0, v[144:145]
	s_mov_b32 m0, s17
	s_nop 0
	global_load_lds_dwordx4 v[220:221], off
	s_mov_b32 m0, s27
	s_nop 0
	global_load_lds_dwordx4 v[222:223], off
	s_waitcnt vmcnt(8)
	s_waitcnt lgkmcnt(0)
	s_nop 0
	s_barrier
	s_waitcnt lgkmcnt(0)
	v_mfma_f32_16x16x32_bf16 v[60:63], v[128:131], v[184:187], v[60:63]
	v_mfma_f32_16x16x32_bf16 v[52:55], v[136:139], v[184:187], v[52:55]
	v_mfma_f32_16x16x32_bf16 v[44:47], v[128:131], v[194:197], v[44:47]
	v_mfma_f32_16x16x32_bf16 v[36:39], v[136:139], v[194:197], v[36:39]
	v_mfma_f32_16x16x32_bf16 v[28:31], v[128:131], v[202:205], v[28:31]
	v_mfma_f32_16x16x32_bf16 v[20:23], v[136:139], v[202:205], v[20:23]
	v_mfma_f32_16x16x32_bf16 v[12:15], v[128:131], v[210:213], v[12:15]
	v_mfma_f32_16x16x32_bf16 v[4:7], v[136:139], v[210:213], v[4:7]
	v_mfma_f32_16x16x32_bf16 v[60:63], v[132:135], v[190:193], v[60:63]
	v_mfma_f32_16x16x32_bf16 v[52:55], v[140:143], v[190:193], v[52:55]
	v_mfma_f32_16x16x32_bf16 v[44:47], v[132:135], v[198:201], v[44:47]
	v_mfma_f32_16x16x32_bf16 v[36:39], v[140:143], v[198:201], v[36:39]
	v_mfma_f32_16x16x32_bf16 v[28:31], v[132:135], v[206:209], v[28:31]
	v_mfma_f32_16x16x32_bf16 v[20:23], v[140:143], v[206:209], v[20:23]
	v_mfma_f32_16x16x32_bf16 v[12:15], v[132:135], v[214:217], v[12:15]
	v_mfma_f32_16x16x32_bf16 v[4:7], v[140:143], v[214:217], v[4:7]
	v_mfma_f32_16x16x32_bf16 v[56:59], v[160:163], v[184:187], v[56:59]
	v_mfma_f32_16x16x32_bf16 v[48:51], v[176:179], v[184:187], v[48:51]
	v_mfma_f32_16x16x32_bf16 v[40:43], v[160:163], v[194:197], v[40:43]
	v_mfma_f32_16x16x32_bf16 v[32:35], v[176:179], v[194:197], v[32:35]
	v_mfma_f32_16x16x32_bf16 v[24:27], v[160:163], v[202:205], v[24:27]
	v_mfma_f32_16x16x32_bf16 v[16:19], v[176:179], v[202:205], v[16:19]
	v_mfma_f32_16x16x32_bf16 v[8:11], v[160:163], v[210:213], v[8:11]
	v_mfma_f32_16x16x32_bf16 v[0:3], v[176:179], v[210:213], v[0:3]
	v_mfma_f32_16x16x32_bf16 v[56:59], v[172:175], v[190:193], v[56:59]
	v_mfma_f32_16x16x32_bf16 v[48:51], v[180:183], v[190:193], v[48:51]
	v_mfma_f32_16x16x32_bf16 v[40:43], v[172:175], v[198:201], v[40:43]
	v_mfma_f32_16x16x32_bf16 v[32:35], v[180:183], v[198:201], v[32:35]
	v_mfma_f32_16x16x32_bf16 v[24:27], v[172:175], v[206:209], v[24:27]
	v_mfma_f32_16x16x32_bf16 v[16:19], v[180:183], v[206:209], v[16:19]
	v_mfma_f32_16x16x32_bf16 v[8:11], v[172:175], v[214:217], v[8:11]
	v_mfma_f32_16x16x32_bf16 v[0:3], v[180:183], v[214:217], v[0:3]
	s_barrier
	s_add_i32 s33, 0, 0x18000
	s_add_i32 s65, 0, 0x1c000
	v_add_u32_e32 v140, s33, v167
	v_add_u32_e32 v180, s65, v167
	ds_read_b128 v[128:131], v140
	ds_read_b128 v[132:135], v140 offset:1024
	ds_read_b128 v[136:139], v140 offset:2048
	ds_read_b128 v[140:143], v140 offset:3072
	ds_read_b128 v[160:163], v180
	ds_read_b128 v[172:175], v180 offset:1024
	ds_read_b128 v[176:179], v180 offset:2048
	ds_read_b128 v[180:183], v180 offset:3072
	s_add_u32 s28, s50, 0x20000
	s_addc_u32 s29, s51, 0
	s_mov_b32 m0, s34
	v_lshl_add_u64 v[224:225], s[28:29], 0, v[144:145]
	ds_read_b128 v[184:187], v171 offset:32768
	ds_read_b128 v[190:193], v171 offset:33792
	ds_read_b128 v[194:197], v171 offset:34816
	ds_read_b128 v[198:201], v171 offset:35840
	ds_read_b128 v[202:205], v171 offset:36864
	ds_read_b128 v[206:209], v171 offset:37888
	ds_read_b128 v[210:213], v171 offset:38912
	ds_read_b128 v[214:217], v171 offset:39936
	global_load_lds_dwordx4 v[224:225], off
	v_lshl_add_u64 v[224:225], s[28:29], 0, v[148:149]
	s_mov_b32 m0, s35
	s_nop 0
	global_load_lds_dwordx4 v[224:225], off
	s_waitcnt vmcnt(8)
	s_waitcnt lgkmcnt(0)
	s_nop 0
	s_barrier
	s_waitcnt lgkmcnt(0)
	v_mfma_f32_16x16x32_bf16 v[124:127], v[128:131], v[184:187], v[124:127]
	v_mfma_f32_16x16x32_bf16 v[120:123], v[136:139], v[184:187], v[120:123]
	v_mfma_f32_16x16x32_bf16 v[116:119], v[128:131], v[194:197], v[116:119]
	v_mfma_f32_16x16x32_bf16 v[112:115], v[136:139], v[194:197], v[112:115]
	v_mfma_f32_16x16x32_bf16 v[92:95], v[128:131], v[202:205], v[92:95]
	v_mfma_f32_16x16x32_bf16 v[84:87], v[136:139], v[202:205], v[84:87]
	v_mfma_f32_16x16x32_bf16 v[76:79], v[128:131], v[210:213], v[76:79]
	v_mfma_f32_16x16x32_bf16 v[68:71], v[136:139], v[210:213], v[68:71]
	v_mfma_f32_16x16x32_bf16 v[124:127], v[132:135], v[190:193], v[124:127]
	v_mfma_f32_16x16x32_bf16 v[120:123], v[140:143], v[190:193], v[120:123]
	v_mfma_f32_16x16x32_bf16 v[116:119], v[132:135], v[198:201], v[116:119]
	v_mfma_f32_16x16x32_bf16 v[112:115], v[140:143], v[198:201], v[112:115]
	v_mfma_f32_16x16x32_bf16 v[92:95], v[132:135], v[206:209], v[92:95]
	v_mfma_f32_16x16x32_bf16 v[84:87], v[140:143], v[206:209], v[84:87]
	v_mfma_f32_16x16x32_bf16 v[76:79], v[132:135], v[214:217], v[76:79]
	v_mfma_f32_16x16x32_bf16 v[68:71], v[140:143], v[214:217], v[68:71]
	v_mfma_f32_16x16x32_bf16 v[108:111], v[160:163], v[184:187], v[108:111]
	v_mfma_f32_16x16x32_bf16 v[104:107], v[176:179], v[184:187], v[104:107]
	v_mfma_f32_16x16x32_bf16 v[100:103], v[160:163], v[194:197], v[100:103]
	v_mfma_f32_16x16x32_bf16 v[96:99], v[176:179], v[194:197], v[96:99]
	v_mfma_f32_16x16x32_bf16 v[88:91], v[160:163], v[202:205], v[88:91]
	v_mfma_f32_16x16x32_bf16 v[80:83], v[176:179], v[202:205], v[80:83]
	v_mfma_f32_16x16x32_bf16 v[72:75], v[160:163], v[210:213], v[72:75]
	v_mfma_f32_16x16x32_bf16 v[64:67], v[176:179], v[210:213], v[64:67]
	v_mfma_f32_16x16x32_bf16 v[108:111], v[172:175], v[190:193], v[108:111]
	v_mfma_f32_16x16x32_bf16 v[104:107], v[180:183], v[190:193], v[104:107]
	v_mfma_f32_16x16x32_bf16 v[100:103], v[172:175], v[198:201], v[100:103]
	v_mfma_f32_16x16x32_bf16 v[96:99], v[180:183], v[198:201], v[96:99]
	v_mfma_f32_16x16x32_bf16 v[88:91], v[172:175], v[206:209], v[88:91]
	v_mfma_f32_16x16x32_bf16 v[80:83], v[180:183], v[206:209], v[80:83]
	v_mfma_f32_16x16x32_bf16 v[72:75], v[172:175], v[214:217], v[72:75]
	v_mfma_f32_16x16x32_bf16 v[64:67], v[180:183], v[214:217], v[64:67]
	s_barrier
	s_add_i32 s28, s33, s13
	v_lshl_add_u64 v[164:165], v[164:165], 0, s[10:11]
	s_mov_b32 m0, s28
	ds_read_b128 v[184:187], v171 offset:49152
	ds_read_b128 v[190:193], v171 offset:50176
	ds_read_b128 v[194:197], v171 offset:51200
	ds_read_b128 v[198:201], v171 offset:52224
	ds_read_b128 v[202:205], v171 offset:53248
	ds_read_b128 v[206:209], v171 offset:54272
	ds_read_b128 v[210:213], v171 offset:55296
	ds_read_b128 v[214:217], v171 offset:56320
	global_load_lds_dwordx4 v[164:165], off
	s_add_i32 m0, s28, 0x2000
	s_add_u32 s28, s46, 0x20080
	v_lshl_add_u64 v[164:165], v[218:219], 0, s[10:11]
	s_addc_u32 s29, s47, 0
	s_add_i32 s33, s65, s13
	global_load_lds_dwordx4 v[164:165], off
	v_lshl_add_u64 v[164:165], s[28:29], 0, v[146:147]
	s_mov_b32 m0, s33
	s_nop 0
	global_load_lds_dwordx4 v[164:165], off
	v_lshl_add_u64 v[164:165], s[28:29], 0, v[150:151]
	s_add_i32 m0, s33, 0x2000
	s_nop 0
	global_load_lds_dwordx4 v[164:165], off
	v_lshl_add_u64 v[164:165], v[220:221], 0, s[10:11]
	s_mov_b32 m0, s52
	s_nop 0
	global_load_lds_dwordx4 v[164:165], off
	v_lshl_add_u64 v[164:165], v[222:223], 0, s[10:11]
	s_mov_b32 m0, s53
	s_nop 0
	global_load_lds_dwordx4 v[164:165], off
	s_waitcnt vmcnt(8)
	s_waitcnt lgkmcnt(0)
	s_barrier
	s_waitcnt lgkmcnt(0)
	v_mfma_f32_16x16x32_bf16 v[60:63], v[128:131], v[184:187], v[60:63]
	v_mfma_f32_16x16x32_bf16 v[52:55], v[136:139], v[184:187], v[52:55]
	v_mfma_f32_16x16x32_bf16 v[44:47], v[128:131], v[194:197], v[44:47]
	v_mfma_f32_16x16x32_bf16 v[36:39], v[136:139], v[194:197], v[36:39]
	v_mfma_f32_16x16x32_bf16 v[28:31], v[128:131], v[202:205], v[28:31]
	v_mfma_f32_16x16x32_bf16 v[20:23], v[136:139], v[202:205], v[20:23]
	v_mfma_f32_16x16x32_bf16 v[12:15], v[128:131], v[210:213], v[12:15]
	v_mfma_f32_16x16x32_bf16 v[4:7], v[136:139], v[210:213], v[4:7]
	v_mfma_f32_16x16x32_bf16 v[60:63], v[132:135], v[190:193], v[60:63]
	v_mfma_f32_16x16x32_bf16 v[52:55], v[140:143], v[190:193], v[52:55]
	v_mfma_f32_16x16x32_bf16 v[44:47], v[132:135], v[198:201], v[44:47]
	v_mfma_f32_16x16x32_bf16 v[36:39], v[140:143], v[198:201], v[36:39]
	v_mfma_f32_16x16x32_bf16 v[28:31], v[132:135], v[206:209], v[28:31]
	v_mfma_f32_16x16x32_bf16 v[20:23], v[140:143], v[206:209], v[20:23]
	v_mfma_f32_16x16x32_bf16 v[12:15], v[132:135], v[214:217], v[12:15]
	v_mfma_f32_16x16x32_bf16 v[4:7], v[140:143], v[214:217], v[4:7]
	v_mfma_f32_16x16x32_bf16 v[56:59], v[160:163], v[184:187], v[56:59]
	v_mfma_f32_16x16x32_bf16 v[48:51], v[176:179], v[184:187], v[48:51]
	v_mfma_f32_16x16x32_bf16 v[40:43], v[160:163], v[194:197], v[40:43]
	v_mfma_f32_16x16x32_bf16 v[32:35], v[176:179], v[194:197], v[32:35]
	v_mfma_f32_16x16x32_bf16 v[24:27], v[160:163], v[202:205], v[24:27]
	v_mfma_f32_16x16x32_bf16 v[16:19], v[176:179], v[202:205], v[16:19]
	v_mfma_f32_16x16x32_bf16 v[8:11], v[160:163], v[210:213], v[8:11]
	v_mfma_f32_16x16x32_bf16 v[0:3], v[176:179], v[210:213], v[0:3]
	v_mfma_f32_16x16x32_bf16 v[56:59], v[172:175], v[190:193], v[56:59]
	v_mfma_f32_16x16x32_bf16 v[48:51], v[180:183], v[190:193], v[48:51]
	v_mfma_f32_16x16x32_bf16 v[40:43], v[172:175], v[198:201], v[40:43]
	v_mfma_f32_16x16x32_bf16 v[32:35], v[180:183], v[198:201], v[32:35]
	v_mfma_f32_16x16x32_bf16 v[24:27], v[172:175], v[206:209], v[24:27]
	v_mfma_f32_16x16x32_bf16 v[16:19], v[180:183], v[206:209], v[16:19]
	v_mfma_f32_16x16x32_bf16 v[8:11], v[172:175], v[214:217], v[8:11]
	v_mfma_f32_16x16x32_bf16 v[0:3], v[180:183], v[214:217], v[0:3]
	s_barrier
	s_add_i32 s64, s64, 2
	s_add_u32 s44, s44, 0x100
	s_addc_u32 s45, s45, 0
	s_add_u32 s62, s62, 0x100
	s_addc_u32 s63, s63, 0
	s_cmp_gt_u32 s64, 5
	s_cbranch_scc0 .LBB0_1029
	s_and_b64 vcc, exec, s[14:15]
	s_cbranch_vccz .LBB0_1032
	s_barrier

.LBB0_1108:
	v_lshl_add_u32 v172, s40, 8, v178
	v_lshl_or_b32 v170, s53, 8, v180
	v_ashrrev_i32_e32 v173, 31, v172
	v_ashrrev_i32_e32 v171, 31, v170
	v_lshlrev_b64 v[128:129], 10, v[172:173]
	v_lshl_add_u64 v[128:129], v[128:129], 0, v[170:171]
	v_lshlrev_b64 v[128:129], 1, v[128:129]
	v_add_u32_e32 v232, 0x40000, v128
	v_add_u32_e32 v233, 0x48000, v128
	v_add_u32_e32 v234, 0x50000, v128
	v_add_u32_e32 v235, 0x58000, v128
	global_load_dword v241, v232, s[30:31]
	global_load_dword v241, v232, s[30:31] offset:256
	global_load_dword v241, v232, s[24:25]
	global_load_dword v241, v232, s[24:25] offset:256
	global_load_dword v241, v233, s[30:31]
	global_load_dword v241, v233, s[30:31] offset:256
	global_load_dword v241, v233, s[24:25]
	global_load_dword v241, v233, s[24:25] offset:256
	global_load_dword v241, v234, s[30:31]
	global_load_dword v241, v234, s[30:31] offset:256
	global_load_dword v241, v234, s[24:25]
	global_load_dword v241, v234, s[24:25] offset:256
	global_load_dword v241, v235, s[30:31]
	global_load_dword v241, v235, s[30:31] offset:256
	global_load_dword v241, v235, s[24:25]
	global_load_dword v241, v235, s[24:25] offset:256
	v_lshl_add_u64 v[130:131], s[30:31], 0, v[128:129]
	global_load_dwordx4 v[184:187], v[130:131], off
	v_lshl_add_u64 v[130:131], s[24:25], 0, v[128:129]
	global_load_dwordx4 v[190:193], v[130:131], off
	v_or_b32_e32 v128, 0x100, v128
	v_or_b32_e32 v226, 16, v172
	v_lshl_add_u64 v[130:131], s[30:31], 0, v[128:129]
	v_lshl_add_u64 v[128:129], s[24:25], 0, v[128:129]
	v_or_b32_e32 v176, 32, v172
	v_or_b32_e32 v174, 48, v172
	v_ashrrev_i32_e32 v227, 31, v226
	global_load_dwordx4 v[194:197], v[130:131], off
	global_load_dwordx4 v[198:201], v[128:129], off
	v_ashrrev_i32_e32 v177, 31, v176
	v_ashrrev_i32_e32 v175, 31, v174
	v_lshlrev_b64 v[130:131], 10, v[226:227]
	v_lshlrev_b64 v[128:129], 11, v[172:173]
	v_lshlrev_b64 v[132:133], 10, v[176:177]
	v_lshlrev_b64 v[134:135], 10, v[174:175]
	v_lshl_add_u64 v[130:131], v[130:131], 0, v[170:171]
	v_lshlrev_b64 v[168:169], 1, v[170:171]
	v_lshl_add_u64 v[128:129], s[24:25], 0, v[128:129]
	v_lshl_add_u64 v[132:133], v[132:133], 0, v[170:171]
	v_lshl_add_u64 v[134:135], v[134:135], 0, v[170:171]
	v_lshlrev_b64 v[130:131], 1, v[130:131]
	v_lshl_add_u64 v[136:137], s[30:31], 0, v[130:131]
	v_lshl_add_u64 v[228:229], v[128:129], 0, v[168:169]
	v_lshlrev_b64 v[128:129], 1, v[132:133]
	v_lshlrev_b64 v[132:133], 1, v[134:135]
	v_lshl_add_u64 v[134:135], s[24:25], 0, v[130:131]
	global_load_dwordx4 v[202:205], v[136:137], off
	global_load_dwordx4 v[206:209], v[134:135], off
	v_or_b32_e32 v130, 0x100, v130
	v_lshl_add_u64 v[136:137], s[30:31], 0, v[128:129]
	v_lshl_add_u64 v[138:139], s[24:25], 0, v[128:129]
	v_or_b32_e32 v128, 0x100, v128
	v_lshl_add_u64 v[134:135], s[30:31], 0, v[132:133]
	v_lshl_add_u64 v[144:145], s[24:25], 0, v[132:133]
	v_or_b32_e32 v132, 0x100, v132
	v_lshl_add_u64 v[146:147], s[30:31], 0, v[130:131]
	v_lshl_add_u64 v[130:131], s[24:25], 0, v[130:131]
	global_load_dwordx4 v[210:213], v[136:137], off
	global_load_dwordx4 v[214:217], v[138:139], off
	v_lshl_add_u64 v[148:149], s[30:31], 0, v[128:129]
	v_lshl_add_u64 v[128:129], s[24:25], 0, v[128:129]
	global_load_dwordx4 v[140:143], v[134:135], off
	global_load_dwordx4 v[136:139], v[144:145], off
	v_lshl_add_u64 v[134:135], s[30:31], 0, v[132:133]
	v_lshl_add_u64 v[230:231], s[24:25], 0, v[132:133]
	global_load_dwordx4 v[218:221], v[146:147], off
	global_load_dwordx4 v[222:225], v[130:131], off
	s_nop 0
	global_load_dwordx4 v[148:151], v[148:149], off
	s_nop 0
	global_load_dwordx4 v[144:147], v[128:129], off
	s_nop 0
	global_load_dwordx4 v[132:135], v[134:135], off
	s_nop 0
	global_load_dwordx4 v[128:131], v[230:231], off
	s_andn2_b64 vcc, exec, s[4:5]
	s_mov_b64 s[4:5], -1
	s_waitcnt vmcnt(0)
	v_lshlrev_b32_e32 v230, 16, v184
	v_and_b32_e32 v231, 0xffff0000, v184
	v_lshlrev_b32_e32 v184, 16, v185
	v_and_b32_e32 v185, 0xffff0000, v185
	v_lshlrev_b32_e32 v232, 16, v186
	v_and_b32_e32 v233, 0xffff0000, v186
	v_lshlrev_b32_e32 v186, 16, v187
	v_and_b32_e32 v187, 0xffff0000, v187
	v_lshlrev_b32_e32 v234, 16, v190
	v_and_b32_e32 v235, 0xffff0000, v190
	v_lshlrev_b32_e32 v190, 16, v191
	v_and_b32_e32 v191, 0xffff0000, v191
	v_lshlrev_b32_e32 v236, 16, v192
	v_and_b32_e32 v237, 0xffff0000, v192
	v_lshlrev_b32_e32 v192, 16, v193
	v_and_b32_e32 v193, 0xffff0000, v193
	v_pk_fma_f32 v[126:127], v[126:127], v[184:185], v[190:191]
	v_pk_fma_f32 v[184:185], v[122:123], v[186:187], v[192:193]
	v_pk_fma_f32 v[122:123], v[120:121], v[232:233], v[236:237]
	v_pk_fma_f32 v[124:125], v[124:125], v[230:231], v[234:235]
	v_lshlrev_b32_e32 v192, 16, v201
	v_cvt_pk_bf16_f32 v120, v124, v125
	v_cvt_pk_bf16_f32 v121, v126, v127
	v_cvt_pk_bf16_f32 v122, v122, v123
	v_cvt_pk_bf16_f32 v123, v184, v185
	global_store_dwordx4 v[228:229], v[120:123], off
	v_lshlrev_b32_e32 v184, 16, v200
	v_and_b32_e32 v185, 0xffff0000, v200
	v_lshlrev_b32_e32 v120, 16, v196
	v_and_b32_e32 v121, 0xffff0000, v196
	v_lshlrev_b32_e32 v122, 16, v197
	v_and_b32_e32 v123, 0xffff0000, v197
	v_and_b32_e32 v193, 0xffff0000, v201
	v_lshlrev_b32_e32 v186, 16, v194
	v_and_b32_e32 v187, 0xffff0000, v194
	v_lshlrev_b32_e32 v190, 16, v195
	v_and_b32_e32 v191, 0xffff0000, v195
	v_lshlrev_b32_e32 v124, 16, v198
	v_and_b32_e32 v125, 0xffff0000, v198
	v_lshlrev_b32_e32 v126, 16, v199
	v_and_b32_e32 v127, 0xffff0000, v199
	v_pk_fma_f32 v[122:123], v[114:115], v[122:123], v[192:193]
	v_pk_fma_f32 v[114:115], v[112:113], v[120:121], v[184:185]
	v_pk_fma_f32 v[118:119], v[118:119], v[190:191], v[126:127]
	v_pk_fma_f32 v[116:117], v[116:117], v[186:187], v[124:125]
	v_lshlrev_b32_e32 v120, 16, v205
	v_cvt_pk_bf16_f32 v112, v116, v117
	v_cvt_pk_bf16_f32 v113, v118, v119
	v_cvt_pk_bf16_f32 v114, v114, v115
	v_cvt_pk_bf16_f32 v115, v122, v123
	global_store_dwordx4 v[228:229], v[112:115], off offset:256
	v_lshlrev_b32_e32 v122, 16, v206
	v_and_b32_e32 v123, 0xffff0000, v206
	v_lshlrev_b32_e32 v114, 16, v202
	v_and_b32_e32 v115, 0xffff0000, v202
	v_lshlrev_b64 v[112:113], 11, v[226:227]
	v_lshlrev_b32_e32 v118, 16, v204
	v_and_b32_e32 v119, 0xffff0000, v204
	v_and_b32_e32 v121, 0xffff0000, v205
	v_lshlrev_b32_e32 v126, 16, v208
	v_and_b32_e32 v127, 0xffff0000, v208
	v_lshlrev_b32_e32 v184, 16, v209
	v_and_b32_e32 v185, 0xffff0000, v209
	v_pk_fma_f32 v[108:109], v[108:109], v[114:115], v[122:123]
	v_lshlrev_b32_e32 v116, 16, v203
	v_and_b32_e32 v117, 0xffff0000, v203
	v_lshlrev_b32_e32 v124, 16, v207
	v_and_b32_e32 v125, 0xffff0000, v207
	v_pk_fma_f32 v[114:115], v[106:107], v[120:121], v[184:185]
	v_pk_fma_f32 v[106:107], v[104:105], v[118:119], v[126:127]
	v_cvt_pk_bf16_f32 v104, v108, v109
	v_lshl_add_u64 v[108:109], s[24:25], 0, v[112:113]
	v_pk_fma_f32 v[110:111], v[110:111], v[116:117], v[124:125]
	v_lshl_add_u64 v[108:109], v[108:109], 0, v[168:169]
	v_cvt_pk_bf16_f32 v105, v110, v111
	v_cvt_pk_bf16_f32 v106, v106, v107
	v_cvt_pk_bf16_f32 v107, v114, v115
	global_store_dwordx4 v[108:109], v[104:107], off
	v_lshlrev_b32_e32 v110, 16, v220
	v_and_b32_e32 v111, 0xffff0000, v220
	v_lshlrev_b32_e32 v104, 16, v218
	v_and_b32_e32 v105, 0xffff0000, v218
	v_lshlrev_b32_e32 v112, 16, v221
	v_and_b32_e32 v113, 0xffff0000, v221
	v_lshlrev_b32_e32 v114, 16, v222
	v_and_b32_e32 v115, 0xffff0000, v222
	v_lshlrev_b32_e32 v118, 16, v224
	v_and_b32_e32 v119, 0xffff0000, v224
	v_lshlrev_b32_e32 v120, 16, v225
	v_and_b32_e32 v121, 0xffff0000, v225
	v_lshlrev_b32_e32 v106, 16, v219
	v_and_b32_e32 v107, 0xffff0000, v219
	v_lshlrev_b32_e32 v116, 16, v223
	v_and_b32_e32 v117, 0xffff0000, v223
	v_pk_fma_f32 v[100:101], v[100:101], v[104:105], v[114:115]
	v_pk_fma_f32 v[104:105], v[98:99], v[112:113], v[120:121]
	v_pk_fma_f32 v[98:99], v[96:97], v[110:111], v[118:119]
	v_pk_fma_f32 v[102:103], v[102:103], v[106:107], v[116:117]
	v_cvt_pk_bf16_f32 v96, v100, v101
	v_lshlrev_b32_e32 v106, 16, v214
	v_cvt_pk_bf16_f32 v97, v102, v103
	v_cvt_pk_bf16_f32 v98, v98, v99
	v_cvt_pk_bf16_f32 v99, v104, v105
	global_store_dwordx4 v[108:109], v[96:99], off offset:256
	v_and_b32_e32 v107, 0xffff0000, v214
	v_lshlrev_b32_e32 v102, 16, v212
	v_lshlrev_b32_e32 v98, 16, v210
	v_and_b32_e32 v99, 0xffff0000, v210
	v_lshlrev_b64 v[96:97], 11, v[176:177]
	v_and_b32_e32 v103, 0xffff0000, v212
	v_lshlrev_b32_e32 v104, 16, v213
	v_and_b32_e32 v105, 0xffff0000, v213
	v_lshlrev_b32_e32 v110, 16, v216
	v_and_b32_e32 v111, 0xffff0000, v216
	v_lshlrev_b32_e32 v112, 16, v217
	v_and_b32_e32 v113, 0xffff0000, v217
	v_pk_fma_f32 v[92:93], v[92:93], v[98:99], v[106:107]
	v_lshlrev_b32_e32 v100, 16, v211
	v_and_b32_e32 v101, 0xffff0000, v211
	v_lshlrev_b32_e32 v108, 16, v215
	v_and_b32_e32 v109, 0xffff0000, v215
	v_pk_fma_f32 v[98:99], v[90:91], v[104:105], v[112:113]
	v_pk_fma_f32 v[90:91], v[88:89], v[102:103], v[110:111]
	v_cvt_pk_bf16_f32 v88, v92, v93
	v_lshl_add_u64 v[92:93], s[24:25], 0, v[96:97]
	v_pk_fma_f32 v[94:95], v[94:95], v[100:101], v[108:109]
	v_lshl_add_u64 v[92:93], v[92:93], 0, v[168:169]
	v_cvt_pk_bf16_f32 v89, v94, v95
	v_cvt_pk_bf16_f32 v90, v90, v91
	v_cvt_pk_bf16_f32 v91, v98, v99
	global_store_dwordx4 v[92:93], v[88:91], off
	v_lshlrev_b32_e32 v94, 16, v150
	v_and_b32_e32 v95, 0xffff0000, v150
	v_lshlrev_b32_e32 v88, 16, v148
	v_and_b32_e32 v89, 0xffff0000, v148
	v_lshlrev_b32_e32 v96, 16, v151
	v_and_b32_e32 v97, 0xffff0000, v151
	v_lshlrev_b32_e32 v98, 16, v144
	v_and_b32_e32 v99, 0xffff0000, v144
	v_lshlrev_b32_e32 v102, 16, v146
	v_and_b32_e32 v103, 0xffff0000, v146
	v_lshlrev_b32_e32 v104, 16, v147
	v_and_b32_e32 v105, 0xffff0000, v147
	v_lshlrev_b32_e32 v90, 16, v149
	v_and_b32_e32 v91, 0xffff0000, v149
	v_lshlrev_b32_e32 v100, 16, v145
	v_and_b32_e32 v101, 0xffff0000, v145
	v_pk_fma_f32 v[84:85], v[84:85], v[88:89], v[98:99]
	v_pk_fma_f32 v[88:89], v[82:83], v[96:97], v[104:105]
	v_pk_fma_f32 v[82:83], v[80:81], v[94:95], v[102:103]
	v_pk_fma_f32 v[86:87], v[86:87], v[90:91], v[100:101]
	v_cvt_pk_bf16_f32 v80, v84, v85
	v_lshlrev_b32_e32 v90, 16, v136
	v_cvt_pk_bf16_f32 v81, v86, v87
	v_cvt_pk_bf16_f32 v82, v82, v83
	v_cvt_pk_bf16_f32 v83, v88, v89
	global_store_dwordx4 v[92:93], v[80:83], off offset:256
	v_and_b32_e32 v91, 0xffff0000, v136
	v_lshlrev_b32_e32 v86, 16, v142
	v_lshlrev_b32_e32 v82, 16, v140
	v_and_b32_e32 v83, 0xffff0000, v140
	v_lshlrev_b64 v[80:81], 11, v[174:175]
	v_and_b32_e32 v87, 0xffff0000, v142
	v_lshlrev_b32_e32 v88, 16, v143
	v_and_b32_e32 v89, 0xffff0000, v143
	v_lshlrev_b32_e32 v94, 16, v138
	v_and_b32_e32 v95, 0xffff0000, v138
	v_lshlrev_b32_e32 v96, 16, v139
	v_and_b32_e32 v97, 0xffff0000, v139
	v_pk_fma_f32 v[76:77], v[76:77], v[82:83], v[90:91]
	v_lshlrev_b32_e32 v84, 16, v141
	v_and_b32_e32 v85, 0xffff0000, v141
	v_lshlrev_b32_e32 v92, 16, v137
	v_and_b32_e32 v93, 0xffff0000, v137
	v_pk_fma_f32 v[82:83], v[74:75], v[88:89], v[96:97]
	v_pk_fma_f32 v[74:75], v[72:73], v[86:87], v[94:95]
	v_cvt_pk_bf16_f32 v72, v76, v77
	v_lshl_add_u64 v[76:77], s[24:25], 0, v[80:81]
	v_pk_fma_f32 v[78:79], v[78:79], v[84:85], v[92:93]
	v_lshl_add_u64 v[76:77], v[76:77], 0, v[168:169]
	v_cvt_pk_bf16_f32 v73, v78, v79
	v_cvt_pk_bf16_f32 v74, v74, v75
	v_cvt_pk_bf16_f32 v75, v82, v83
	global_store_dwordx4 v[76:77], v[72:75], off
	v_lshlrev_b32_e32 v78, 16, v134
	v_and_b32_e32 v79, 0xffff0000, v134
	v_lshlrev_b32_e32 v72, 16, v132
	v_and_b32_e32 v73, 0xffff0000, v132
	v_lshlrev_b32_e32 v74, 16, v133
	v_and_b32_e32 v75, 0xffff0000, v133
	v_lshlrev_b32_e32 v80, 16, v135
	v_and_b32_e32 v81, 0xffff0000, v135
	v_lshlrev_b32_e32 v82, 16, v128
	v_and_b32_e32 v83, 0xffff0000, v128
	v_lshlrev_b32_e32 v84, 16, v129
	v_and_b32_e32 v85, 0xffff0000, v129
	v_lshlrev_b32_e32 v86, 16, v130
	v_and_b32_e32 v87, 0xffff0000, v130
	v_lshlrev_b32_e32 v88, 16, v131
	v_and_b32_e32 v89, 0xffff0000, v131
	v_add_u32_e32 v132, 0x80, v172
	v_pk_fma_f32 v[70:71], v[70:71], v[74:75], v[84:85]
	v_pk_fma_f32 v[68:69], v[68:69], v[72:73], v[82:83]
	v_pk_fma_f32 v[72:73], v[66:67], v[80:81], v[88:89]
	v_pk_fma_f32 v[66:67], v[64:65], v[78:79], v[86:87]
	v_cvt_pk_bf16_f32 v64, v68, v69
	v_cvt_pk_bf16_f32 v65, v70, v71
	v_ashrrev_i32_e32 v133, 31, v132
	v_cvt_pk_bf16_f32 v66, v66, v67
	v_cvt_pk_bf16_f32 v67, v72, v73
	global_store_dwordx4 v[76:77], v[64:67], off offset:256
	v_add_u32_e32 v134, 0x90, v172
	v_ashrrev_i32_e32 v135, 31, v134
	v_lshlrev_b64 v[64:65], 10, v[132:133]
	v_lshl_add_u64 v[64:65], v[64:65], 0, v[170:171]
	v_lshlrev_b64 v[64:65], 1, v[64:65]
	v_lshl_add_u64 v[66:67], s[30:31], 0, v[64:65]
	global_load_dwordx4 v[100:103], v[66:67], off
	v_lshl_add_u64 v[66:67], s[24:25], 0, v[64:65]
	global_load_dwordx4 v[104:107], v[66:67], off
	v_or_b32_e32 v64, 0x100, v64
	v_lshl_add_u64 v[66:67], s[30:31], 0, v[64:65]
	v_lshl_add_u64 v[64:65], s[24:25], 0, v[64:65]
	global_load_dwordx4 v[108:111], v[66:67], off
	global_load_dwordx4 v[112:115], v[64:65], off
	v_lshlrev_b64 v[64:65], 10, v[134:135]
	v_lshl_add_u64 v[64:65], v[64:65], 0, v[170:171]
	v_lshlrev_b64 v[64:65], 1, v[64:65]
	v_lshl_add_u64 v[66:67], s[30:31], 0, v[64:65]
	v_lshl_add_u64 v[68:69], s[24:25], 0, v[64:65]
	global_load_dwordx4 v[116:119], v[66:67], off
	global_load_dwordx4 v[120:123], v[68:69], off
	v_or_b32_e32 v64, 0x100, v64
	v_add_u32_e32 v98, 0xa0, v172
	v_lshl_add_u64 v[66:67], s[30:31], 0, v[64:65]
	v_lshl_add_u64 v[64:65], s[24:25], 0, v[64:65]
	v_ashrrev_i32_e32 v99, 31, v98
	global_load_dwordx4 v[124:127], v[66:67], off
	global_load_dwordx4 v[128:131], v[64:65], off
	v_lshlrev_b64 v[64:65], 10, v[98:99]
	v_lshl_add_u64 v[64:65], v[64:65], 0, v[170:171]
	v_lshlrev_b64 v[64:65], 1, v[64:65]
	v_lshl_add_u64 v[66:67], s[30:31], 0, v[64:65]
	v_lshl_add_u64 v[68:69], s[24:25], 0, v[64:65]
	global_load_dwordx4 v[92:95], v[66:67], off
	global_load_dwordx4 v[88:91], v[68:69], off
	v_or_b32_e32 v64, 0x100, v64
	v_add_u32_e32 v96, 0xb0, v172
	v_lshl_add_u64 v[66:67], s[30:31], 0, v[64:65]
	v_lshl_add_u64 v[64:65], s[24:25], 0, v[64:65]
	v_ashrrev_i32_e32 v97, 31, v96
	global_load_dwordx4 v[84:87], v[66:67], off
	global_load_dwordx4 v[80:83], v[64:65], off
	v_lshlrev_b64 v[64:65], 10, v[96:97]
	v_lshl_add_u64 v[64:65], v[64:65], 0, v[170:171]
	v_lshlrev_b64 v[64:65], 1, v[64:65]
	v_lshl_add_u64 v[66:67], s[30:31], 0, v[64:65]
	v_lshl_add_u64 v[68:69], s[24:25], 0, v[64:65]
	global_load_dwordx4 v[76:79], v[66:67], off
	global_load_dwordx4 v[72:75], v[68:69], off
	v_or_b32_e32 v64, 0x100, v64
	v_lshl_add_u64 v[66:67], s[30:31], 0, v[64:65]
	v_lshl_add_u64 v[64:65], s[24:25], 0, v[64:65]
	global_load_dwordx4 v[68:71], v[66:67], off
	s_nop 0
	global_load_dwordx4 v[64:67], v[64:65], off
	v_lshlrev_b64 v[132:133], 11, v[132:133]
	s_waitcnt vmcnt(15)
	v_lshlrev_b32_e32 v136, 16, v100
	v_and_b32_e32 v137, 0xffff0000, v100
	s_waitcnt vmcnt(14)
	v_lshlrev_b32_e32 v140, 16, v104
	v_and_b32_e32 v141, 0xffff0000, v104
	v_lshlrev_b32_e32 v100, 16, v101
	v_and_b32_e32 v101, 0xffff0000, v101
	v_lshlrev_b32_e32 v138, 16, v102
	v_and_b32_e32 v139, 0xffff0000, v102
	v_lshlrev_b32_e32 v102, 16, v103
	v_and_b32_e32 v103, 0xffff0000, v103
	v_lshlrev_b32_e32 v104, 16, v105
	v_and_b32_e32 v105, 0xffff0000, v105
	v_lshlrev_b32_e32 v142, 16, v106
	v_and_b32_e32 v143, 0xffff0000, v106
	v_lshlrev_b32_e32 v106, 16, v107
	v_and_b32_e32 v107, 0xffff0000, v107
	v_pk_fma_f32 v[60:61], v[60:61], v[136:137], v[140:141]
	v_pk_fma_f32 v[62:63], v[62:63], v[100:101], v[104:105]
	v_pk_fma_f32 v[100:101], v[58:59], v[102:103], v[106:107]
	v_pk_fma_f32 v[58:59], v[56:57], v[138:139], v[142:143]
	v_cvt_pk_bf16_f32 v56, v60, v61
	v_lshl_add_u64 v[60:61], s[24:25], 0, v[132:133]
	v_cvt_pk_bf16_f32 v57, v62, v63
	v_cvt_pk_bf16_f32 v58, v58, v59
	v_cvt_pk_bf16_f32 v59, v100, v101
	v_lshl_add_u64 v[60:61], v[60:61], 0, v[168:169]
	global_store_dwordx4 v[60:61], v[56:59], off
	s_waitcnt vmcnt(14)
	v_lshlrev_b32_e32 v62, 16, v110
	v_and_b32_e32 v63, 0xffff0000, v110
	v_lshlrev_b32_e32 v56, 16, v108
	v_and_b32_e32 v57, 0xffff0000, v108
	v_lshlrev_b32_e32 v58, 16, v109
	v_and_b32_e32 v59, 0xffff0000, v109
	v_lshlrev_b32_e32 v100, 16, v111
	v_and_b32_e32 v101, 0xffff0000, v111
	s_waitcnt vmcnt(13)
	v_lshlrev_b32_e32 v102, 16, v112
	v_and_b32_e32 v103, 0xffff0000, v112
	v_lshlrev_b32_e32 v106, 16, v114
	v_and_b32_e32 v107, 0xffff0000, v114
	v_lshlrev_b32_e32 v108, 16, v115
	v_and_b32_e32 v109, 0xffff0000, v115
	v_lshlrev_b32_e32 v104, 16, v113
	v_and_b32_e32 v105, 0xffff0000, v113
	v_pk_fma_f32 v[52:53], v[52:53], v[56:57], v[102:103]
	v_pk_fma_f32 v[56:57], v[50:51], v[100:101], v[108:109]
	v_pk_fma_f32 v[50:51], v[48:49], v[62:63], v[106:107]
	v_pk_fma_f32 v[54:55], v[54:55], v[58:59], v[104:105]
	v_cvt_pk_bf16_f32 v48, v52, v53
	s_waitcnt vmcnt(11)
	v_lshlrev_b32_e32 v58, 16, v120
	v_cvt_pk_bf16_f32 v49, v54, v55
	v_cvt_pk_bf16_f32 v50, v50, v51
	v_cvt_pk_bf16_f32 v51, v56, v57
	global_store_dwordx4 v[60:61], v[48:51], off offset:256
	v_and_b32_e32 v59, 0xffff0000, v120
	v_lshlrev_b32_e32 v54, 16, v118
	v_lshlrev_b32_e32 v50, 16, v116
	v_and_b32_e32 v51, 0xffff0000, v116
	v_lshlrev_b64 v[48:49], 11, v[134:135]
	v_and_b32_e32 v55, 0xffff0000, v118
	v_lshlrev_b32_e32 v56, 16, v119
	v_and_b32_e32 v57, 0xffff0000, v119
	v_lshlrev_b32_e32 v62, 16, v122
	v_and_b32_e32 v63, 0xffff0000, v122
	v_lshlrev_b32_e32 v100, 16, v123
	v_and_b32_e32 v101, 0xffff0000, v123
	v_pk_fma_f32 v[44:45], v[44:45], v[50:51], v[58:59]
	v_lshlrev_b32_e32 v52, 16, v117
	v_and_b32_e32 v53, 0xffff0000, v117
	v_lshlrev_b32_e32 v60, 16, v121
	v_and_b32_e32 v61, 0xffff0000, v121
	v_pk_fma_f32 v[50:51], v[42:43], v[56:57], v[100:101]
	v_pk_fma_f32 v[42:43], v[40:41], v[54:55], v[62:63]
	v_cvt_pk_bf16_f32 v40, v44, v45
	v_lshl_add_u64 v[44:45], s[24:25], 0, v[48:49]
	v_pk_fma_f32 v[46:47], v[46:47], v[52:53], v[60:61]
	v_lshl_add_u64 v[44:45], v[44:45], 0, v[168:169]
	v_cvt_pk_bf16_f32 v41, v46, v47
	v_cvt_pk_bf16_f32 v42, v42, v43
	v_cvt_pk_bf16_f32 v43, v50, v51
	global_store_dwordx4 v[44:45], v[40:43], off
	s_waitcnt vmcnt(12)
	v_lshlrev_b32_e32 v46, 16, v126
	v_and_b32_e32 v47, 0xffff0000, v126
	v_lshlrev_b32_e32 v40, 16, v124
	v_and_b32_e32 v41, 0xffff0000, v124
	v_lshlrev_b32_e32 v48, 16, v127
	v_and_b32_e32 v49, 0xffff0000, v127
	s_waitcnt vmcnt(11)
	v_lshlrev_b32_e32 v50, 16, v128
	v_and_b32_e32 v51, 0xffff0000, v128
	v_lshlrev_b32_e32 v54, 16, v130
	v_and_b32_e32 v55, 0xffff0000, v130
	v_lshlrev_b32_e32 v56, 16, v131
	v_and_b32_e32 v57, 0xffff0000, v131
	v_lshlrev_b32_e32 v42, 16, v125
	v_and_b32_e32 v43, 0xffff0000, v125
	v_lshlrev_b32_e32 v52, 16, v129
	v_and_b32_e32 v53, 0xffff0000, v129
	v_pk_fma_f32 v[36:37], v[36:37], v[40:41], v[50:51]
	v_pk_fma_f32 v[40:41], v[34:35], v[48:49], v[56:57]
	v_pk_fma_f32 v[34:35], v[32:33], v[46:47], v[54:55]
	v_pk_fma_f32 v[38:39], v[38:39], v[42:43], v[52:53]
	v_cvt_pk_bf16_f32 v32, v36, v37
	s_waitcnt vmcnt(9)
	v_lshlrev_b32_e32 v42, 16, v88
	v_cvt_pk_bf16_f32 v33, v38, v39
	v_cvt_pk_bf16_f32 v34, v34, v35
	v_cvt_pk_bf16_f32 v35, v40, v41
	global_store_dwordx4 v[44:45], v[32:35], off offset:256
	v_and_b32_e32 v43, 0xffff0000, v88
	v_lshlrev_b32_e32 v38, 16, v94
	v_lshlrev_b32_e32 v34, 16, v92
	v_and_b32_e32 v35, 0xffff0000, v92
	v_lshlrev_b64 v[32:33], 11, v[98:99]
	v_and_b32_e32 v39, 0xffff0000, v94
	v_lshlrev_b32_e32 v40, 16, v95
	v_and_b32_e32 v41, 0xffff0000, v95
	v_lshlrev_b32_e32 v46, 16, v90
	v_and_b32_e32 v47, 0xffff0000, v90
	v_lshlrev_b32_e32 v48, 16, v91
	v_and_b32_e32 v49, 0xffff0000, v91
	v_pk_fma_f32 v[28:29], v[28:29], v[34:35], v[42:43]
	v_lshlrev_b32_e32 v36, 16, v93
	v_and_b32_e32 v37, 0xffff0000, v93
	v_lshlrev_b32_e32 v44, 16, v89
	v_and_b32_e32 v45, 0xffff0000, v89
	v_pk_fma_f32 v[34:35], v[26:27], v[40:41], v[48:49]
	v_pk_fma_f32 v[26:27], v[24:25], v[38:39], v[46:47]
	v_cvt_pk_bf16_f32 v24, v28, v29
	v_lshl_add_u64 v[28:29], s[24:25], 0, v[32:33]
	v_pk_fma_f32 v[30:31], v[30:31], v[36:37], v[44:45]
	v_lshl_add_u64 v[28:29], v[28:29], 0, v[168:169]
	v_cvt_pk_bf16_f32 v25, v30, v31
	v_cvt_pk_bf16_f32 v26, v26, v27
	v_cvt_pk_bf16_f32 v27, v34, v35
	global_store_dwordx4 v[28:29], v[24:27], off
	s_waitcnt vmcnt(10)
	v_lshlrev_b32_e32 v30, 16, v86
	v_and_b32_e32 v31, 0xffff0000, v86
	v_lshlrev_b32_e32 v24, 16, v84
	v_and_b32_e32 v25, 0xffff0000, v84
	v_lshlrev_b32_e32 v32, 16, v87
	v_and_b32_e32 v33, 0xffff0000, v87
	s_waitcnt vmcnt(9)
	v_lshlrev_b32_e32 v34, 16, v80
	v_and_b32_e32 v35, 0xffff0000, v80
	v_lshlrev_b32_e32 v38, 16, v82
	v_and_b32_e32 v39, 0xffff0000, v82
	v_lshlrev_b32_e32 v40, 16, v83
	v_and_b32_e32 v41, 0xffff0000, v83
	v_lshlrev_b32_e32 v26, 16, v85
	v_and_b32_e32 v27, 0xffff0000, v85
	v_lshlrev_b32_e32 v36, 16, v81
	v_and_b32_e32 v37, 0xffff0000, v81
	v_pk_fma_f32 v[20:21], v[20:21], v[24:25], v[34:35]
	v_pk_fma_f32 v[24:25], v[18:19], v[32:33], v[40:41]
	v_pk_fma_f32 v[18:19], v[16:17], v[30:31], v[38:39]
	v_pk_fma_f32 v[22:23], v[22:23], v[26:27], v[36:37]
	v_cvt_pk_bf16_f32 v16, v20, v21
	s_waitcnt vmcnt(7)
	v_lshlrev_b32_e32 v26, 16, v72
	v_cvt_pk_bf16_f32 v17, v22, v23
	v_cvt_pk_bf16_f32 v18, v18, v19
	v_cvt_pk_bf16_f32 v19, v24, v25
	global_store_dwordx4 v[28:29], v[16:19], off offset:256
	v_and_b32_e32 v27, 0xffff0000, v72
	v_lshlrev_b32_e32 v22, 16, v78
	v_lshlrev_b32_e32 v18, 16, v76
	v_and_b32_e32 v19, 0xffff0000, v76
	v_lshlrev_b64 v[16:17], 11, v[96:97]
	v_and_b32_e32 v23, 0xffff0000, v78
	v_lshlrev_b32_e32 v24, 16, v79
	v_and_b32_e32 v25, 0xffff0000, v79
	v_lshlrev_b32_e32 v30, 16, v74
	v_and_b32_e32 v31, 0xffff0000, v74
	v_lshlrev_b32_e32 v32, 16, v75
	v_and_b32_e32 v33, 0xffff0000, v75
	v_pk_fma_f32 v[12:13], v[12:13], v[18:19], v[26:27]
	v_lshlrev_b32_e32 v20, 16, v77
	v_and_b32_e32 v21, 0xffff0000, v77
	v_lshlrev_b32_e32 v28, 16, v73
	v_and_b32_e32 v29, 0xffff0000, v73
	v_pk_fma_f32 v[18:19], v[10:11], v[24:25], v[32:33]
	v_pk_fma_f32 v[10:11], v[8:9], v[22:23], v[30:31]
	v_cvt_pk_bf16_f32 v8, v12, v13
	v_lshl_add_u64 v[12:13], s[24:25], 0, v[16:17]
	v_pk_fma_f32 v[14:15], v[14:15], v[20:21], v[28:29]
	v_lshl_add_u64 v[12:13], v[12:13], 0, v[168:169]
	v_cvt_pk_bf16_f32 v9, v14, v15
	v_cvt_pk_bf16_f32 v10, v10, v11
	v_cvt_pk_bf16_f32 v11, v18, v19
	global_store_dwordx4 v[12:13], v[8:11], off
	s_waitcnt vmcnt(8)
	v_lshlrev_b32_e32 v14, 16, v70
	v_and_b32_e32 v15, 0xffff0000, v70
	v_lshlrev_b32_e32 v8, 16, v68
	v_and_b32_e32 v9, 0xffff0000, v68
	v_lshlrev_b32_e32 v16, 16, v71
	v_and_b32_e32 v17, 0xffff0000, v71
	s_waitcnt vmcnt(7)
	v_lshlrev_b32_e32 v18, 16, v64
	v_and_b32_e32 v19, 0xffff0000, v64
	v_lshlrev_b32_e32 v22, 16, v66
	v_and_b32_e32 v23, 0xffff0000, v66
	v_lshlrev_b32_e32 v24, 16, v67
	v_and_b32_e32 v25, 0xffff0000, v67
	v_lshlrev_b32_e32 v10, 16, v69
	v_and_b32_e32 v11, 0xffff0000, v69
	v_lshlrev_b32_e32 v20, 16, v65
	v_and_b32_e32 v21, 0xffff0000, v65
	v_pk_fma_f32 v[4:5], v[4:5], v[8:9], v[18:19]
	v_pk_fma_f32 v[8:9], v[2:3], v[16:17], v[24:25]
	v_pk_fma_f32 v[2:3], v[0:1], v[14:15], v[22:23]
	v_pk_fma_f32 v[6:7], v[6:7], v[10:11], v[20:21]
	v_cvt_pk_bf16_f32 v0, v4, v5
	s_nop 0
	v_cvt_pk_bf16_f32 v1, v6, v7
	v_cvt_pk_bf16_f32 v2, v2, v3
	v_cvt_pk_bf16_f32 v3, v8, v9
	global_store_dwordx4 v[12:13], v[0:3], off offset:256
	s_cbranch_vccnz .LBB0_1097
	s_andn2_b64 vcc, exec, s[0:1]
	s_cbranch_vccnz .LBB0_1096
	s_barrier
	s_branch .LBB0_1096
